# residual epilogues: EpiResidNorm x2 and last-layer EpiResid loads 15-16 deep with counted vmcnt, 8 slot loads as two dwordx4; MLA K/V prefetch; padded
# speedup vs baseline: 1.0059x; 1.0059x over previous
.LBB0_1000:
	s_lshl_b32 s0, s4, 5
	s_lshl_b32 s5, s53, 8
	s_lshl_b32 s1, s8, 8
	s_add_i32 s2, s5, s36
	s_or_b32 s0, s1, s0
	s_cmp_gt_i32 s53, 15
	v_lshl_or_b32 v162, v152, 3, s0
	s_cselect_b32 s0, 0x3000, 0
	s_lshl_b32 s12, s0, 2
	v_readlane_b32 s0, v255, 2
	v_readlane_b32 s1, v255, 3
	s_add_u32 s0, s0, s12
	v_ashrrev_i32_e32 v163, 31, v162
	s_addc_u32 s1, s1, 0
	v_lshlrev_b64 v[146:147], 2, v[162:163]
	v_lshl_add_u64 v[130:131], s[0:1], 0, v[146:147]
	s_movk_i32 s0, 0x4000
	v_or_b32_e32 v148, s2, v148
	v_lshl_add_u64 v[134:135], v[130:131], 0, s[26:27]
	v_add_co_u32_e32 v130, vcc, s0, v130
	v_ashrrev_i32_e32 v149, 31, v148
	v_readlane_b32 s0, v254, 61
	v_lshlrev_b64 v[150:151], 13, v[148:149]
	v_readlane_b32 s1, v254, 62
	v_addc_co_u32_e32 v131, vcc, 0, v131, vcc
	s_nop 0
	v_lshl_add_u64 v[150:151], s[0:1], 0, v[150:151]
	v_lshl_add_u64 v[150:151], v[150:151], 0, v[146:147]
	s_waitcnt vmcnt(0)
	s_barrier
	global_load_dwordx4 v[142:145], v[130:131], off
	global_load_dwordx4 v[138:141], v[134:135], off offset:16
	s_nop 0
	global_load_dwordx4 v[130:133], v[134:135], off offset:528
	s_nop 0
	global_load_dwordx4 v[134:137], v[134:135], off offset:512
	s_nop 0
	global_load_dwordx4 v[178:181], v[150:151], off offset:16
	global_load_dwordx4 v[182:185], v[150:151], off
	global_load_dwordx4 v[186:189], v[150:151], off offset:528
	global_load_dwordx4 v[190:193], v[150:151], off offset:512
	v_add_co_u32_e32 v164, vcc, 0x20000, v150
	s_nop 1
	v_addc_co_u32_e32 v165, vcc, 0, v151, vcc
	global_load_dwordx4 v[198:201], v[164:165], off offset:16
	global_load_dwordx4 v[202:205], v[164:165], off
	global_load_dwordx4 v[206:209], v[164:165], off offset:528
	global_load_dwordx4 v[214:217], v[164:165], off offset:512
	v_add_co_u32_e32 v164, vcc, 0x40000, v150
	s_nop 1
	v_addc_co_u32_e32 v165, vcc, 0, v151, vcc
	global_load_dwordx4 v[218:221], v[164:165], off offset:16
	global_load_dwordx4 v[222:225], v[164:165], off
	global_load_dwordx4 v[226:229], v[164:165], off offset:528
	global_load_dwordx4 v[230:233], v[164:165], off offset:512
	v_add_co_u32_e32 v164, vcc, 0x60000, v150
	s_nop 1
	v_addc_co_u32_e32 v165, vcc, 0, v151, vcc
	global_load_dwordx4 v[234:237], v[164:165], off offset:16
	global_load_dwordx4 v[238:241], v[164:165], off
	global_load_dwordx4 v[242:245], v[164:165], off offset:528
	global_load_dwordx4 v[154:157], v[164:165], off offset:512
	s_waitcnt vmcnt(15)
	v_pk_fma_f32 v[108:109], v[108:109], v[140:141], v[180:181]
	v_pk_fma_f32 v[106:107], v[106:107], v[138:139], v[178:179]
	v_add_co_u32_e32 v164, vcc, 0x100000, v150
	s_nop 1
	v_addc_co_u32_e32 v165, vcc, 0, v151, vcc
	global_load_dwordx4 v[178:181], v[164:165], off
	s_waitcnt vmcnt(15)
	v_pk_fma_f32 v[112:113], v[112:113], v[144:145], v[184:185]
	v_pk_fma_f32 v[110:111], v[110:111], v[142:143], v[182:183]
	global_load_dwordx4 v[182:185], v[164:165], off offset:16
	s_waitcnt vmcnt(15)
	v_pk_fma_f32 v[0:1], v[0:1], v[130:131], v[186:187]
	v_pk_fma_f32 v[2:3], v[2:3], v[132:133], v[188:189]
	global_load_dwordx4 v[186:189], v[164:165], off offset:528
	s_waitcnt vmcnt(15)
	v_pk_fma_f32 v[6:7], v[6:7], v[136:137], v[192:193]
	v_pk_fma_f32 v[4:5], v[4:5], v[134:135], v[190:191]
	global_load_dwordx4 v[190:193], v[164:165], off offset:512
	s_waitcnt vmcnt(15)
	v_pk_fma_f32 v[116:117], v[116:117], v[140:141], v[200:201]
	v_pk_fma_f32 v[114:115], v[114:115], v[138:139], v[198:199]
	v_add_co_u32_e32 v164, vcc, 0x120000, v150
	s_nop 1
	v_addc_co_u32_e32 v165, vcc, 0, v151, vcc
	global_load_dwordx4 v[198:201], v[164:165], off
	s_waitcnt vmcnt(15)
	v_pk_fma_f32 v[120:121], v[120:121], v[144:145], v[204:205]
	v_pk_fma_f32 v[118:119], v[118:119], v[142:143], v[202:203]
	global_load_dwordx4 v[202:205], v[164:165], off offset:16
	s_waitcnt vmcnt(15)
	v_pk_fma_f32 v[8:9], v[8:9], v[130:131], v[206:207]
	v_pk_fma_f32 v[10:11], v[10:11], v[132:133], v[208:209]
	global_load_dwordx4 v[206:209], v[164:165], off offset:528
	s_waitcnt vmcnt(15)
	v_pk_fma_f32 v[14:15], v[14:15], v[136:137], v[216:217]
	v_pk_fma_f32 v[12:13], v[12:13], v[134:135], v[214:215]
	global_load_dwordx4 v[214:217], v[164:165], off offset:512
	s_waitcnt vmcnt(15)
	v_pk_fma_f32 v[124:125], v[124:125], v[140:141], v[220:221]
	v_pk_fma_f32 v[122:123], v[122:123], v[138:139], v[218:219]
	v_add_co_u32_e32 v164, vcc, 0x140000, v150
	s_nop 1
	v_addc_co_u32_e32 v165, vcc, 0, v151, vcc
	global_load_dwordx4 v[218:221], v[164:165], off
	s_waitcnt vmcnt(15)
	v_pk_fma_f32 v[128:129], v[128:129], v[144:145], v[224:225]
	v_pk_fma_f32 v[126:127], v[126:127], v[142:143], v[222:223]
	global_load_dwordx4 v[222:225], v[164:165], off offset:16
	s_waitcnt vmcnt(15)
	v_pk_fma_f32 v[20:21], v[20:21], v[130:131], v[226:227]
	v_pk_fma_f32 v[22:23], v[22:23], v[132:133], v[228:229]
	global_load_dwordx4 v[226:229], v[164:165], off offset:528
	s_waitcnt vmcnt(15)
	v_pk_fma_f32 v[26:27], v[26:27], v[136:137], v[232:233]
	v_pk_fma_f32 v[24:25], v[24:25], v[134:135], v[230:231]
	global_load_dwordx4 v[230:233], v[164:165], off offset:512
	s_waitcnt vmcnt(15)
	v_pk_fma_f32 v[90:91], v[90:91], v[140:141], v[236:237]
	v_pk_fma_f32 v[88:89], v[88:89], v[138:139], v[234:235]
	v_add_co_u32_e32 v164, vcc, 0x160000, v150
	s_nop 1
	v_addc_co_u32_e32 v165, vcc, 0, v151, vcc
	global_load_dwordx4 v[234:237], v[164:165], off
	s_waitcnt vmcnt(15)
	v_pk_fma_f32 v[94:95], v[94:95], v[144:145], v[240:241]
	v_pk_fma_f32 v[92:93], v[92:93], v[142:143], v[238:239]
	global_load_dwordx4 v[238:241], v[164:165], off offset:16
	s_waitcnt vmcnt(15)
	v_pk_fma_f32 v[34:35], v[34:35], v[132:133], v[244:245]
	v_pk_fma_f32 v[32:33], v[32:33], v[130:131], v[242:243]
	global_load_dwordx4 v[242:245], v[164:165], off offset:528
	s_waitcnt vmcnt(15)
	v_pk_fma_f32 v[42:43], v[42:43], v[136:137], v[156:157]
	v_pk_fma_f32 v[40:41], v[40:41], v[134:135], v[154:155]
	global_load_dwordx4 v[154:157], v[164:165], off offset:512
	s_waitcnt vmcnt(15)
	v_pk_fma_f32 v[104:105], v[104:105], v[144:145], v[180:181]
	v_pk_fma_f32 v[102:103], v[102:103], v[142:143], v[178:179]
	s_waitcnt vmcnt(14)
	v_pk_fma_f32 v[100:101], v[100:101], v[140:141], v[184:185]
	v_pk_fma_f32 v[98:99], v[98:99], v[138:139], v[182:183]
	s_waitcnt vmcnt(13)
	v_pk_fma_f32 v[56:57], v[56:57], v[130:131], v[186:187]
	v_pk_fma_f32 v[58:59], v[58:59], v[132:133], v[188:189]
	s_waitcnt vmcnt(12)
	v_pk_fma_f32 v[62:63], v[62:63], v[136:137], v[192:193]
	v_pk_fma_f32 v[60:61], v[60:61], v[134:135], v[190:191]
	s_waitcnt vmcnt(11)
	v_pk_fma_f32 v[86:87], v[86:87], v[144:145], v[200:201]
	v_pk_fma_f32 v[84:85], v[84:85], v[142:143], v[198:199]
	s_waitcnt vmcnt(10)
	v_pk_fma_f32 v[82:83], v[82:83], v[140:141], v[204:205]
	v_pk_fma_f32 v[80:81], v[80:81], v[138:139], v[202:203]
	s_waitcnt vmcnt(9)
	v_pk_fma_f32 v[72:73], v[72:73], v[130:131], v[206:207]
	v_pk_fma_f32 v[74:75], v[74:75], v[132:133], v[208:209]
	s_waitcnt vmcnt(8)
	v_pk_fma_f32 v[78:79], v[78:79], v[136:137], v[216:217]
	v_pk_fma_f32 v[76:77], v[76:77], v[134:135], v[214:215]
	s_waitcnt vmcnt(7)
	v_pk_fma_f32 v[70:71], v[70:71], v[144:145], v[220:221]
	v_pk_fma_f32 v[68:69], v[68:69], v[142:143], v[218:219]
	s_waitcnt vmcnt(6)
	v_pk_fma_f32 v[66:67], v[66:67], v[140:141], v[224:225]
	v_pk_fma_f32 v[64:65], v[64:65], v[138:139], v[222:223]
	s_waitcnt vmcnt(5)
	v_pk_fma_f32 v[50:51], v[50:51], v[132:133], v[228:229]
	v_pk_fma_f32 v[48:49], v[48:49], v[130:131], v[226:227]
	s_waitcnt vmcnt(4)
	v_pk_fma_f32 v[54:55], v[54:55], v[136:137], v[232:233]
	v_pk_fma_f32 v[52:53], v[52:53], v[134:135], v[230:231]
	s_waitcnt vmcnt(3)
	v_pk_fma_f32 v[46:47], v[46:47], v[144:145], v[236:237]
	v_pk_fma_f32 v[44:45], v[44:45], v[142:143], v[234:235]
	s_waitcnt vmcnt(2)
	v_pk_fma_f32 v[38:39], v[38:39], v[140:141], v[240:241]
	v_pk_fma_f32 v[36:37], v[36:37], v[138:139], v[238:239]
	s_waitcnt vmcnt(1)
	v_pk_fma_f32 v[18:19], v[18:19], v[132:133], v[244:245]
	v_pk_fma_f32 v[16:17], v[16:17], v[130:131], v[242:243]
	s_waitcnt vmcnt(0)
	v_pk_fma_f32 v[28:29], v[28:29], v[134:135], v[154:155]
	v_pk_fma_f32 v[30:31], v[30:31], v[136:137], v[156:157]
	s_mov_b64 s[0:1], 0x160000
	s_branch .Lmy_pad_1
	s_nop 0
	s_nop 0
	s_nop 0
	s_nop 0
	s_nop 0
	s_nop 0
	s_nop 0
	s_nop 0
	s_nop 0
	s_nop 0
	s_nop 0
	s_nop 0
	s_nop 0
	s_nop 0
	s_nop 0
	s_nop 0
	s_nop 0
	s_nop 0
	s_nop 0
	s_nop 0
	s_nop 0
	s_nop 0
	s_nop 0
	s_nop 0
	s_nop 0
	s_nop 0
	s_nop 0
	s_nop 0
	s_nop 0
	s_nop 0
	s_nop 0
	s_nop 0
	s_nop 0
	s_nop 0
	s_nop 0
	s_nop 0
	s_nop 0
	s_nop 0
	s_nop 0
	s_nop 0
	s_nop 0
	s_nop 0
	s_nop 0
	s_nop 0
	s_nop 0
	s_nop 0
	s_nop 0
	s_nop 0

.LBB0_1027:
	s_waitcnt vmcnt(0) lgkmcnt(0)
	s_barrier
	s_and_saveexec_b64 s[8:9], s[0:1]
	s_cbranch_execz .LBB0_1029
	v_readlane_b32 s0, v252, 37
	v_lshlrev_b64 v[130:131], 5, v[130:131]
	v_readlane_b32 s1, v252, 38
	s_nop 1
	v_lshl_add_u64 v[130:131], s[0:1], 0, v[130:131]
	global_load_dwordx4 v[178:181], v[130:131], off sc1
	global_load_dwordx4 v[182:185], v[130:131], off offset:16 sc1
	s_waitcnt vmcnt(0)
	v_add_f32_e32 v96, 0, v178
	v_add_f32_e32 v96, v96, v179
	v_add_f32_e32 v96, v96, v180
	v_add_f32_e32 v96, v96, v181
	v_add_f32_e32 v96, v96, v182
	v_add_f32_e32 v96, v96, v183
	v_add_f32_e32 v96, v96, v184
	v_add_f32_e32 v96, v96, v185
	v_fmamk_f32 v96, v96, 0x3a000000, v196
	v_rsq_f32_e32 v96, v96
	v_lshl_add_u32 v130, v132, 2, 0
	ds_write_b32 v130, v96 offset:8192

.LBB0_1364:
	s_lshl_b32 s0, s4, 5
	s_lshl_b32 s5, s51, 8
	s_lshl_b32 s1, s8, 8
	s_add_i32 s2, s5, s36
	s_or_b32 s0, s1, s0
	s_cmp_gt_i32 s51, 15
	v_lshl_or_b32 v162, v152, 3, s0
	s_cselect_b32 s0, 0x3000, 0
	v_or_b32_e32 v148, s2, v148
	s_lshl_b32 s12, s0, 2
	v_ashrrev_i32_e32 v149, 31, v148
	s_add_u32 s0, s49, s12
	v_ashrrev_i32_e32 v163, 31, v162
	v_lshlrev_b64 v[150:151], 13, v[148:149]
	s_addc_u32 s1, s50, 0
	v_lshlrev_b64 v[146:147], 2, v[162:163]
	v_lshl_add_u64 v[150:151], s[96:97], 0, v[150:151]
	v_lshl_add_u64 v[134:135], s[0:1], 0, v[146:147]
	v_lshl_add_u64 v[150:151], v[150:151], 0, v[146:147]
	s_waitcnt vmcnt(0)
	s_barrier
	global_load_dwordx4 v[138:141], v[134:135], off offset:16
	global_load_dwordx4 v[142:145], v[134:135], off
	global_load_dwordx4 v[130:133], v[134:135], off offset:528
	s_nop 0
	global_load_dwordx4 v[134:137], v[134:135], off offset:512
	s_nop 0
	global_load_dwordx4 v[178:181], v[150:151], off offset:16
	global_load_dwordx4 v[182:185], v[150:151], off
	global_load_dwordx4 v[186:189], v[150:151], off offset:528
	global_load_dwordx4 v[190:193], v[150:151], off offset:512
	v_add_co_u32_e32 v164, vcc, 0x20000, v150
	s_nop 1
	v_addc_co_u32_e32 v165, vcc, 0, v151, vcc
	global_load_dwordx4 v[198:201], v[164:165], off offset:16
	global_load_dwordx4 v[202:205], v[164:165], off
	global_load_dwordx4 v[206:209], v[164:165], off offset:528
	global_load_dwordx4 v[214:217], v[164:165], off offset:512
	v_add_co_u32_e32 v164, vcc, 0x40000, v150
	s_nop 1
	v_addc_co_u32_e32 v165, vcc, 0, v151, vcc
	global_load_dwordx4 v[218:221], v[164:165], off offset:16
	global_load_dwordx4 v[222:225], v[164:165], off
	global_load_dwordx4 v[226:229], v[164:165], off offset:528
	global_load_dwordx4 v[230:233], v[164:165], off offset:512
	v_add_co_u32_e32 v164, vcc, 0x60000, v150
	s_nop 1
	v_addc_co_u32_e32 v165, vcc, 0, v151, vcc
	global_load_dwordx4 v[234:237], v[164:165], off offset:16
	global_load_dwordx4 v[238:241], v[164:165], off
	global_load_dwordx4 v[242:245], v[164:165], off offset:528
	global_load_dwordx4 v[154:157], v[164:165], off offset:512
	s_waitcnt vmcnt(15)
	v_pk_fma_f32 v[108:109], v[108:109], v[140:141], v[180:181]
	v_pk_fma_f32 v[106:107], v[106:107], v[138:139], v[178:179]
	v_add_co_u32_e32 v164, vcc, 0x100000, v150
	s_nop 1
	v_addc_co_u32_e32 v165, vcc, 0, v151, vcc
	global_load_dwordx4 v[178:181], v[164:165], off
	s_waitcnt vmcnt(15)
	v_pk_fma_f32 v[112:113], v[112:113], v[144:145], v[184:185]
	v_pk_fma_f32 v[110:111], v[110:111], v[142:143], v[182:183]
	global_load_dwordx4 v[182:185], v[164:165], off offset:16
	s_waitcnt vmcnt(15)
	v_pk_fma_f32 v[0:1], v[0:1], v[130:131], v[186:187]
	v_pk_fma_f32 v[2:3], v[2:3], v[132:133], v[188:189]
	global_load_dwordx4 v[186:189], v[164:165], off offset:528
	s_waitcnt vmcnt(15)
	v_pk_fma_f32 v[6:7], v[6:7], v[136:137], v[192:193]
	v_pk_fma_f32 v[4:5], v[4:5], v[134:135], v[190:191]
	global_load_dwordx4 v[190:193], v[164:165], off offset:512
	s_waitcnt vmcnt(15)
	v_pk_fma_f32 v[116:117], v[116:117], v[140:141], v[200:201]
	v_pk_fma_f32 v[114:115], v[114:115], v[138:139], v[198:199]
	v_add_co_u32_e32 v164, vcc, 0x120000, v150
	s_nop 1
	v_addc_co_u32_e32 v165, vcc, 0, v151, vcc
	global_load_dwordx4 v[198:201], v[164:165], off
	s_waitcnt vmcnt(15)
	v_pk_fma_f32 v[120:121], v[120:121], v[144:145], v[204:205]
	v_pk_fma_f32 v[118:119], v[118:119], v[142:143], v[202:203]
	global_load_dwordx4 v[202:205], v[164:165], off offset:16
	s_waitcnt vmcnt(15)
	v_pk_fma_f32 v[8:9], v[8:9], v[130:131], v[206:207]
	v_pk_fma_f32 v[10:11], v[10:11], v[132:133], v[208:209]
	global_load_dwordx4 v[206:209], v[164:165], off offset:528
	s_waitcnt vmcnt(15)
	v_pk_fma_f32 v[14:15], v[14:15], v[136:137], v[216:217]
	v_pk_fma_f32 v[12:13], v[12:13], v[134:135], v[214:215]
	global_load_dwordx4 v[214:217], v[164:165], off offset:512
	s_waitcnt vmcnt(15)
	v_pk_fma_f32 v[124:125], v[124:125], v[140:141], v[220:221]
	v_pk_fma_f32 v[122:123], v[122:123], v[138:139], v[218:219]
	v_add_co_u32_e32 v164, vcc, 0x140000, v150
	s_nop 1
	v_addc_co_u32_e32 v165, vcc, 0, v151, vcc
	global_load_dwordx4 v[218:221], v[164:165], off
	s_waitcnt vmcnt(15)
	v_pk_fma_f32 v[128:129], v[128:129], v[144:145], v[224:225]
	v_pk_fma_f32 v[126:127], v[126:127], v[142:143], v[222:223]
	global_load_dwordx4 v[222:225], v[164:165], off offset:16
	s_waitcnt vmcnt(15)
	v_pk_fma_f32 v[20:21], v[20:21], v[130:131], v[226:227]
	v_pk_fma_f32 v[22:23], v[22:23], v[132:133], v[228:229]
	global_load_dwordx4 v[226:229], v[164:165], off offset:528
	s_waitcnt vmcnt(15)
	v_pk_fma_f32 v[26:27], v[26:27], v[136:137], v[232:233]
	v_pk_fma_f32 v[24:25], v[24:25], v[134:135], v[230:231]
	global_load_dwordx4 v[230:233], v[164:165], off offset:512
	s_waitcnt vmcnt(15)
	v_pk_fma_f32 v[90:91], v[90:91], v[140:141], v[236:237]
	v_pk_fma_f32 v[88:89], v[88:89], v[138:139], v[234:235]
	v_add_co_u32_e32 v164, vcc, 0x160000, v150
	s_nop 1
	v_addc_co_u32_e32 v165, vcc, 0, v151, vcc
	global_load_dwordx4 v[234:237], v[164:165], off
	s_waitcnt vmcnt(15)
	v_pk_fma_f32 v[94:95], v[94:95], v[144:145], v[240:241]
	v_pk_fma_f32 v[92:93], v[92:93], v[142:143], v[238:239]
	global_load_dwordx4 v[238:241], v[164:165], off offset:16
	s_waitcnt vmcnt(15)
	v_pk_fma_f32 v[38:39], v[38:39], v[132:133], v[244:245]
	v_pk_fma_f32 v[36:37], v[36:37], v[130:131], v[242:243]
	global_load_dwordx4 v[242:245], v[164:165], off offset:528
	s_waitcnt vmcnt(15)
	v_pk_fma_f32 v[42:43], v[42:43], v[136:137], v[156:157]
	v_pk_fma_f32 v[40:41], v[40:41], v[134:135], v[154:155]
	global_load_dwordx4 v[154:157], v[164:165], off offset:512
	s_waitcnt vmcnt(15)
	v_pk_fma_f32 v[104:105], v[104:105], v[144:145], v[180:181]
	v_pk_fma_f32 v[102:103], v[102:103], v[142:143], v[178:179]
	s_waitcnt vmcnt(14)
	v_pk_fma_f32 v[100:101], v[100:101], v[140:141], v[184:185]
	v_pk_fma_f32 v[98:99], v[98:99], v[138:139], v[182:183]
	s_waitcnt vmcnt(13)
	v_pk_fma_f32 v[56:57], v[56:57], v[130:131], v[186:187]
	v_pk_fma_f32 v[58:59], v[58:59], v[132:133], v[188:189]
	s_waitcnt vmcnt(12)
	v_pk_fma_f32 v[62:63], v[62:63], v[136:137], v[192:193]
	v_pk_fma_f32 v[60:61], v[60:61], v[134:135], v[190:191]
	s_waitcnt vmcnt(11)
	v_pk_fma_f32 v[86:87], v[86:87], v[144:145], v[200:201]
	v_pk_fma_f32 v[84:85], v[84:85], v[142:143], v[198:199]
	s_waitcnt vmcnt(10)
	v_pk_fma_f32 v[82:83], v[82:83], v[140:141], v[204:205]
	v_pk_fma_f32 v[80:81], v[80:81], v[138:139], v[202:203]
	s_waitcnt vmcnt(9)
	v_pk_fma_f32 v[72:73], v[72:73], v[130:131], v[206:207]
	v_pk_fma_f32 v[74:75], v[74:75], v[132:133], v[208:209]
	s_waitcnt vmcnt(8)
	v_pk_fma_f32 v[78:79], v[78:79], v[136:137], v[216:217]
	v_pk_fma_f32 v[76:77], v[76:77], v[134:135], v[214:215]
	s_waitcnt vmcnt(7)
	v_pk_fma_f32 v[70:71], v[70:71], v[144:145], v[220:221]
	v_pk_fma_f32 v[68:69], v[68:69], v[142:143], v[218:219]
	s_waitcnt vmcnt(6)
	v_pk_fma_f32 v[66:67], v[66:67], v[140:141], v[224:225]
	v_pk_fma_f32 v[64:65], v[64:65], v[138:139], v[222:223]
	s_waitcnt vmcnt(5)
	v_pk_fma_f32 v[50:51], v[50:51], v[132:133], v[228:229]
	v_pk_fma_f32 v[48:49], v[48:49], v[130:131], v[226:227]
	s_waitcnt vmcnt(4)
	v_pk_fma_f32 v[54:55], v[54:55], v[136:137], v[232:233]
	v_pk_fma_f32 v[52:53], v[52:53], v[134:135], v[230:231]
	s_waitcnt vmcnt(3)
	v_pk_fma_f32 v[46:47], v[46:47], v[144:145], v[236:237]
	v_pk_fma_f32 v[44:45], v[44:45], v[142:143], v[234:235]
	s_waitcnt vmcnt(2)
	v_pk_fma_f32 v[34:35], v[34:35], v[140:141], v[240:241]
	v_pk_fma_f32 v[32:33], v[32:33], v[138:139], v[238:239]
	s_waitcnt vmcnt(1)
	v_pk_fma_f32 v[18:19], v[18:19], v[132:133], v[244:245]
	v_pk_fma_f32 v[16:17], v[16:17], v[130:131], v[242:243]
	s_waitcnt vmcnt(0)
	v_pk_fma_f32 v[28:29], v[28:29], v[134:135], v[154:155]
	v_pk_fma_f32 v[30:31], v[30:31], v[136:137], v[156:157]
	s_mov_b64 s[0:1], 0x160000
	s_branch .Lmy_pad_0
	s_nop 0
	s_nop 0
	s_nop 0
	s_nop 0
	s_nop 0
	s_nop 0
	s_nop 0
	s_nop 0
	s_nop 0
	s_nop 0
	s_nop 0
	s_nop 0
	s_nop 0
	s_nop 0
	s_nop 0
	s_nop 0
	s_nop 0
	s_nop 0
	s_nop 0
	s_nop 0
	s_nop 0
	s_nop 0
	s_nop 0
	s_nop 0
	s_nop 0
	s_nop 0
	s_nop 0
	s_nop 0
	s_nop 0
	s_nop 0
	s_nop 0
	s_nop 0
	s_nop 0
	s_nop 0
	s_nop 0
	s_nop 0
	s_nop 0
	s_nop 0
	s_nop 0
	s_nop 0
	s_nop 0
	s_nop 0
	s_nop 0
	s_nop 0
	s_nop 0
	s_nop 0
	s_nop 0
	s_nop 0

.LBB0_1416:
	s_cmp_lt_i32 s43, 32
	v_lshl_add_u32 v164, s43, 8, v154
	v_lshl_or_b32 v162, s44, 8, v156
	s_cselect_b32 s2, s87, 0x6000
	s_cselect_b32 s22, s68, s96
	s_cselect_b32 s23, s69, s97
	s_cmp_gt_i32 s43, 15
	v_ashrrev_i32_e32 v165, 31, v164
	s_cselect_b32 s2, s2, 0
	v_ashrrev_i32_e32 v163, 31, v162
	v_lshlrev_b64 v[132:133], 11, v[164:165]
	s_lshl_b32 s2, s2, 2
	v_lshl_add_u64 v[132:133], v[132:133], 0, v[162:163]
	s_add_u32 s2, s49, s2
	v_lshlrev_b64 v[152:153], 2, v[132:133]
	s_addc_u32 s3, s50, 0
	v_lshl_add_u64 v[166:167], s[96:97], 0, v[152:153]
	v_lshl_add_u64 v[130:131], v[162:163], 2, s[2:3]
	global_load_dwordx4 v[142:145], v[130:131], off
	global_load_dwordx4 v[138:141], v[130:131], off offset:64
	global_load_dwordx4 v[134:137], v[130:131], off offset:512
	global_load_dwordx4 v[130:133], v[130:131], off offset:576
	v_lshl_add_u64 v[168:169], s[22:23], 0, v[152:153]
	s_and_b64 vcc, exec, s[0:1]
	s_mov_b64 s[0:1], -1
	v_mov_b64_e32 v[240:241], v[166:167]
	global_load_dwordx4 v[220:223], v[240:241], off
	global_load_dwordx4 v[224:227], v[240:241], off offset:64
	global_load_dwordx4 v[228:231], v[240:241], off offset:512
	global_load_dwordx4 v[232:235], v[240:241], off offset:576
	s_mov_b64 s[2:3], 0x20000
	v_lshl_add_u64 v[240:241], v[166:167], 0, s[2:3]
	global_load_dwordx4 v[236:239], v[240:241], off
	global_load_dwordx4 v[170:173], v[240:241], off offset:64
	global_load_dwordx4 v[174:177], v[240:241], off offset:512
	global_load_dwordx4 v[178:181], v[240:241], off offset:576
	s_mov_b64 s[2:3], 0x40000
	v_lshl_add_u64 v[240:241], v[166:167], 0, s[2:3]
	global_load_dwordx4 v[182:185], v[240:241], off
	global_load_dwordx4 v[186:189], v[240:241], off offset:64
	global_load_dwordx4 v[190:193], v[240:241], off offset:512
	global_load_dwordx4 v[202:205], v[240:241], off offset:576
	s_mov_b64 s[2:3], 0x60000
	v_lshl_add_u64 v[240:241], v[166:167], 0, s[2:3]
	global_load_dwordx4 v[206:209], v[240:241], off
	global_load_dwordx4 v[214:217], v[240:241], off offset:64
	global_load_dwordx4 v[158:161], v[240:241], off offset:512
	s_waitcnt vmcnt(14)
	v_pk_fma_f32 v[222:223], v[128:129], v[144:145], v[222:223]
	v_pk_fma_f32 v[220:221], v[126:127], v[142:143], v[220:221]
	v_mov_b64_e32 v[242:243], v[168:169]
	global_store_dwordx4 v[242:243], v[220:223], off
	s_nop 1
	global_load_dwordx4 v[220:223], v[240:241], off offset:576
	s_waitcnt vmcnt(15)
	v_pk_fma_f32 v[226:227], v[124:125], v[140:141], v[226:227]
	v_pk_fma_f32 v[224:225], v[122:123], v[138:139], v[224:225]
	global_store_dwordx4 v[242:243], v[224:227], off offset:64
	s_mov_b64 s[2:3], 0x100000
	v_lshl_add_u64 v[240:241], v[166:167], 0, s[2:3]
	global_load_dwordx4 v[224:227], v[240:241], off
	s_waitcnt vmcnt(16)
	v_pk_fma_f32 v[230:231], v[120:121], v[136:137], v[230:231]
	v_pk_fma_f32 v[228:229], v[118:119], v[134:135], v[228:229]
	global_store_dwordx4 v[242:243], v[228:231], off offset:512
	s_nop 1
	global_load_dwordx4 v[228:231], v[240:241], off offset:64
	s_waitcnt vmcnt(17)
	v_pk_fma_f32 v[234:235], v[108:109], v[132:133], v[234:235]
	v_pk_fma_f32 v[232:233], v[106:107], v[130:131], v[232:233]
	global_store_dwordx4 v[242:243], v[232:235], off offset:576
	s_nop 1
	global_load_dwordx4 v[232:235], v[240:241], off offset:512
	s_waitcnt vmcnt(18)
	v_pk_fma_f32 v[238:239], v[116:117], v[144:145], v[238:239]
	v_pk_fma_f32 v[236:237], v[114:115], v[142:143], v[236:237]
	s_mov_b64 s[2:3], 0x20000
	v_lshl_add_u64 v[242:243], v[168:169], 0, s[2:3]
	global_store_dwordx4 v[242:243], v[236:239], off
	s_nop 1
	global_load_dwordx4 v[236:239], v[240:241], off offset:576
	s_waitcnt vmcnt(19)
	v_pk_fma_f32 v[172:173], v[112:113], v[140:141], v[172:173]
	v_pk_fma_f32 v[170:171], v[110:111], v[138:139], v[170:171]
	global_store_dwordx4 v[242:243], v[170:173], off offset:64
	s_mov_b64 s[2:3], 0x120000
	v_lshl_add_u64 v[240:241], v[166:167], 0, s[2:3]
	global_load_dwordx4 v[170:173], v[240:241], off
	s_waitcnt vmcnt(20)
	v_pk_fma_f32 v[176:177], v[104:105], v[136:137], v[176:177]
	v_pk_fma_f32 v[174:175], v[102:103], v[134:135], v[174:175]
	global_store_dwordx4 v[242:243], v[174:177], off offset:512
	s_nop 1
	global_load_dwordx4 v[174:177], v[240:241], off offset:64
	s_waitcnt vmcnt(21)
	v_pk_fma_f32 v[180:181], v[90:91], v[132:133], v[180:181]
	v_pk_fma_f32 v[178:179], v[88:89], v[130:131], v[178:179]
	global_store_dwordx4 v[242:243], v[178:181], off offset:576
	s_nop 1
	global_load_dwordx4 v[178:181], v[240:241], off offset:512
	s_waitcnt vmcnt(22)
	v_pk_fma_f32 v[184:185], v[100:101], v[144:145], v[184:185]
	v_pk_fma_f32 v[182:183], v[98:99], v[142:143], v[182:183]
	s_mov_b64 s[2:3], 0x40000
	v_lshl_add_u64 v[242:243], v[168:169], 0, s[2:3]
	global_store_dwordx4 v[242:243], v[182:185], off
	s_nop 1
	global_load_dwordx4 v[182:185], v[240:241], off offset:576
	s_waitcnt vmcnt(23)
	v_pk_fma_f32 v[188:189], v[94:95], v[140:141], v[188:189]
	v_pk_fma_f32 v[186:187], v[92:93], v[138:139], v[186:187]
	global_store_dwordx4 v[242:243], v[186:189], off offset:64
	s_mov_b64 s[2:3], 0x140000
	v_lshl_add_u64 v[240:241], v[166:167], 0, s[2:3]
	global_load_dwordx4 v[186:189], v[240:241], off
	s_waitcnt vmcnt(24)
	v_pk_fma_f32 v[192:193], v[86:87], v[136:137], v[192:193]
	v_pk_fma_f32 v[190:191], v[84:85], v[134:135], v[190:191]
	global_store_dwordx4 v[242:243], v[190:193], off offset:512
	s_nop 1
	global_load_dwordx4 v[190:193], v[240:241], off offset:64
	s_waitcnt vmcnt(25)
	v_pk_fma_f32 v[204:205], v[74:75], v[132:133], v[204:205]
	v_pk_fma_f32 v[202:203], v[72:73], v[130:131], v[202:203]
	global_store_dwordx4 v[242:243], v[202:205], off offset:576
	s_nop 1
	global_load_dwordx4 v[202:205], v[240:241], off offset:512
	s_waitcnt vmcnt(26)
	v_pk_fma_f32 v[208:209], v[82:83], v[144:145], v[208:209]
	v_pk_fma_f32 v[206:207], v[80:81], v[142:143], v[206:207]
	s_mov_b64 s[2:3], 0x60000
	v_lshl_add_u64 v[242:243], v[168:169], 0, s[2:3]
	global_store_dwordx4 v[242:243], v[206:209], off
	s_nop 1
	global_load_dwordx4 v[206:209], v[240:241], off offset:576
	s_waitcnt vmcnt(27)
	v_pk_fma_f32 v[216:217], v[78:79], v[140:141], v[216:217]
	v_pk_fma_f32 v[214:215], v[76:77], v[138:139], v[214:215]
	global_store_dwordx4 v[242:243], v[214:217], off offset:64
	s_mov_b64 s[2:3], 0x160000
	v_lshl_add_u64 v[240:241], v[166:167], 0, s[2:3]
	global_load_dwordx4 v[214:217], v[240:241], off
	s_waitcnt vmcnt(28)
	v_pk_fma_f32 v[160:161], v[70:71], v[136:137], v[160:161]
	v_pk_fma_f32 v[158:159], v[68:69], v[134:135], v[158:159]
	global_store_dwordx4 v[242:243], v[158:161], off offset:512
	s_nop 1
	global_load_dwordx4 v[158:161], v[240:241], off offset:64
	s_waitcnt vmcnt(28)
	v_pk_fma_f32 v[222:223], v[66:67], v[132:133], v[222:223]
	v_pk_fma_f32 v[220:221], v[64:65], v[130:131], v[220:221]
	global_store_dwordx4 v[242:243], v[220:223], off offset:576
	s_nop 1
	global_load_dwordx4 v[220:223], v[240:241], off offset:512
	s_waitcnt vmcnt(28)
	v_pk_fma_f32 v[226:227], v[62:63], v[144:145], v[226:227]
	v_pk_fma_f32 v[224:225], v[60:61], v[142:143], v[224:225]
	s_mov_b64 s[2:3], 0x100000
	v_lshl_add_u64 v[242:243], v[168:169], 0, s[2:3]
	global_store_dwordx4 v[242:243], v[224:227], off
	s_nop 1
	global_load_dwordx4 v[224:227], v[240:241], off offset:576
	s_waitcnt vmcnt(28)
	v_pk_fma_f32 v[230:231], v[58:59], v[140:141], v[230:231]
	v_pk_fma_f32 v[228:229], v[56:57], v[138:139], v[228:229]
	global_store_dwordx4 v[242:243], v[228:231], off offset:64
	s_waitcnt vmcnt(27)
	v_pk_fma_f32 v[234:235], v[54:55], v[136:137], v[234:235]
	v_pk_fma_f32 v[232:233], v[52:53], v[134:135], v[232:233]
	global_store_dwordx4 v[242:243], v[232:235], off offset:512
	s_waitcnt vmcnt(26)
	v_pk_fma_f32 v[238:239], v[42:43], v[132:133], v[238:239]
	v_pk_fma_f32 v[236:237], v[40:41], v[130:131], v[236:237]
	global_store_dwordx4 v[242:243], v[236:239], off offset:576
	s_waitcnt vmcnt(25)
	v_pk_fma_f32 v[172:173], v[50:51], v[144:145], v[172:173]
	v_pk_fma_f32 v[170:171], v[48:49], v[142:143], v[170:171]
	s_mov_b64 s[2:3], 0x120000
	v_lshl_add_u64 v[242:243], v[168:169], 0, s[2:3]
	global_store_dwordx4 v[242:243], v[170:173], off
	s_waitcnt vmcnt(24)
	v_pk_fma_f32 v[176:177], v[46:47], v[140:141], v[176:177]
	v_pk_fma_f32 v[174:175], v[44:45], v[138:139], v[174:175]
	global_store_dwordx4 v[242:243], v[174:177], off offset:64
	s_waitcnt vmcnt(23)
	v_pk_fma_f32 v[180:181], v[38:39], v[136:137], v[180:181]
	v_pk_fma_f32 v[178:179], v[36:37], v[134:135], v[178:179]
	global_store_dwordx4 v[242:243], v[178:181], off offset:512
	s_waitcnt vmcnt(22)
	v_pk_fma_f32 v[184:185], v[26:27], v[132:133], v[184:185]
	v_pk_fma_f32 v[182:183], v[24:25], v[130:131], v[182:183]
	global_store_dwordx4 v[242:243], v[182:185], off offset:576
	s_waitcnt vmcnt(21)
	v_pk_fma_f32 v[188:189], v[34:35], v[144:145], v[188:189]
	v_pk_fma_f32 v[186:187], v[32:33], v[142:143], v[186:187]
	s_mov_b64 s[2:3], 0x140000
	v_lshl_add_u64 v[242:243], v[168:169], 0, s[2:3]
	global_store_dwordx4 v[242:243], v[186:189], off
	s_waitcnt vmcnt(20)
	v_pk_fma_f32 v[192:193], v[30:31], v[140:141], v[192:193]
	v_pk_fma_f32 v[190:191], v[28:29], v[138:139], v[190:191]
	global_store_dwordx4 v[242:243], v[190:193], off offset:64
	s_waitcnt vmcnt(19)
	v_pk_fma_f32 v[204:205], v[22:23], v[136:137], v[204:205]
	v_pk_fma_f32 v[202:203], v[20:21], v[134:135], v[202:203]
	global_store_dwordx4 v[242:243], v[202:205], off offset:512
	s_waitcnt vmcnt(18)
	v_pk_fma_f32 v[208:209], v[10:11], v[132:133], v[208:209]
	v_pk_fma_f32 v[206:207], v[8:9], v[130:131], v[206:207]
	global_store_dwordx4 v[242:243], v[206:209], off offset:576
	s_waitcnt vmcnt(17)
	v_pk_fma_f32 v[216:217], v[18:19], v[144:145], v[216:217]
	v_pk_fma_f32 v[214:215], v[16:17], v[142:143], v[214:215]
	s_mov_b64 s[2:3], 0x160000
	v_lshl_add_u64 v[242:243], v[168:169], 0, s[2:3]
	global_store_dwordx4 v[242:243], v[214:217], off
	s_waitcnt vmcnt(16)
	v_pk_fma_f32 v[160:161], v[14:15], v[140:141], v[160:161]
	v_pk_fma_f32 v[158:159], v[12:13], v[138:139], v[158:159]
	global_store_dwordx4 v[242:243], v[158:161], off offset:64
	s_waitcnt vmcnt(15)
	v_pk_fma_f32 v[222:223], v[6:7], v[136:137], v[222:223]
	v_pk_fma_f32 v[220:221], v[4:5], v[134:135], v[220:221]
	global_store_dwordx4 v[242:243], v[220:223], off offset:512
	s_waitcnt vmcnt(14)
	v_pk_fma_f32 v[226:227], v[2:3], v[132:133], v[226:227]
	v_pk_fma_f32 v[224:225], v[0:1], v[130:131], v[224:225]
	global_store_dwordx4 v[242:243], v[224:227], off offset:576
	s_mov_b64 s[2:3], 0x160000
	s_cbranch_vccnz .LBB0_1401
	s_andn2_b64 vcc, exec, s[8:9]
	s_cbranch_vccnz .LBB0_1400
	s_barrier
	s_branch .LBB0_1400
